# alternate CUs (bid>>3 odd) enter P1 ~5 us later so that the epilogue store bursts of the two CU groups fall into each other's K-loops
# baseline (speedup 1.0000x reference)
; #define PG8_STAGE(bufoff, gbase, voff) do { _Pragma("unroll") for (int _i = 0; _i < 2; ++_i) \
;         __builtin_amdgcn_global_load_lds((const unsigned*)((const char*)(gbase) + (voff)[_i]), (PG8_LAS unsigned*)(lds + (bufoff) + ldsw + _i * 8192), 16, 0, 0); } while (0)
; #define PG8_BAR __builtin_amdgcn_s_barrier()
; template <class Epi, class Sched, bool ALIGN_EPI = false, bool SP2 = false>
; __device__ __forceinline__ void gemm_phase(PG8_LAS unsigned char* lds, const Gemm g, const Sched& S, const Epi& E) {
;     const int tid = threadIdx.x, wid = __builtin_amdgcn_readfirstlane(tid >> 6), lane = tid & 63, wr = wid >> 2, wc = wid & 3, fr = lane & 15, fq = lane >> 4;
;     const int K = g.K, nt = K / BK;
;     unsigned voffA[2], voffB[2];
; #pragma unroll
;     for (int i = 0; i < 2; ++i) { int R, C; stage_rc(tid * 16 + i * 8192, R, C); const int Rb = Epi::PERM ? ((R & ~31) + perm32(R & 31)) : R;
;         voffA[i] = (unsigned)(R * K + C) * 2u; voffB[i] = (unsigned)(Rb * K + C) * 2u; }
;     const size_t kstep = (size_t)(BK * 2);
;     const size_t hstep = (size_t)HALF * K * 2;
;     const size_t tstep = 2 * hstep;
;     const unsigned ldsw = (unsigned)wid * 1024u;
;     const int aoff = lds_byte(wr * 64 + fr, fq * 8), boff = lds_byte(wc * 32 + fr, fq * 8);
;     ...
;     const char* cA = (const char*)g.A + (size_t)cur.pm * tstep; const char* cB = (const char*)g.Bt + (size_t)cur.pn * tstep;
;     S.a_ready(cur);
;     if constexpr (SP2) {
;         PG8_STAGE(PG8_SB(0, 0), cB, voffB); PG8_STAGE(PG8_SB(0, 1), cB + hstep, voffB); PG8_STAGE(PG8_SA(0, 0), cA, voffA); PG8_STAGE(PG8_SA(0, 1), cA + hstep, voffA);
;         if (wr == 1) PG8_BAR;
.LBB0_153:
	s_andn2_b64 vcc, exec, s[0:1]
	s_cbranch_vccnz .LBB0_209
	s_lshr_b32 s94, s2, 3
	s_and_b32 s94, s94, 1
	s_cmp_eq_u32 s94, 0
	s_cbranch_scc1 .Lp1_nodelay
	s_mov_b32 s95, 5
.Lp1_delay:
	s_sleep 31
	s_sub_u32 s95, s95, 1
	s_cmp_lg_u32 s95, 0
	s_cbranch_scc1 .Lp1_delay
.Lp1_nodelay:
	v_lshlrev_b32_e32 v1, 4, v0
	v_and_b32_e32 v2, 32, v0
	v_bitop3_b32 v3, v1, v2, 48 bitop3:0x6c
	v_lshrrev_b32_e32 v2, 1, v0
	v_lshrrev_b32_e32 v5, 5, v0
	s_add_u32 s68, s22, 0x2000000
	v_and_b32_e32 v2, 24, v2
	v_and_b32_e32 v5, 4, v5
	v_bfe_u32 v6, v0, 2, 2
	s_addc_u32 s69, s23, 0
	v_bfe_u32 v13, v0, 2, 4
	v_and_b32_e32 v12, 64, v0
	v_or3_b32 v5, v5, v6, v2
	v_lshrrev_b32_e32 v6, 3, v0
	v_or_b32_e32 v14, 0x2000, v1
	s_add_u32 s70, s22, 0x1000000
	v_or_b32_e32 v4, v3, v12
	v_and_or_b32 v7, v6, 48, v13
	v_and_or_b32 v6, v6, 32, v5
	v_lshrrev_b32_e32 v1, 7, v14
	s_movk_i32 s0, 0x70
	s_addc_u32 s71, s23, 0
	v_lshl_or_b32 v148, v6, 11, v4
	v_and_or_b32 v6, v1, s0, v13
	s_movk_i32 s0, 0x60
	s_lshr_b32 s1, s14, 6
	s_ashr_i32 s5, s4, 31
	s_ashr_i32 s47, s46, 31
	v_and_or_b32 v1, v1, s0, v5
	s_lshr_b32 s0, s14, 8
	s_lshl_b32 s72, s1, 10
	s_lshl_b64 s[10:11], s[4:5], 19
	s_lshl_b64 s[12:13], s[46:47], 19
	s_add_u32 s50, s70, s12
	s_addc_u32 s51, s71, s13
	s_add_i32 s47, s72, 0
	s_add_i32 m0, s47, 0x10000
	v_lshl_or_b32 v152, v1, 11, v4
	global_load_lds_dwordx4 v148, s[50:51]
	s_add_i32 m0, s47, 0x12000
	s_add_u32 s12, s50, 0x40000
	global_load_lds_dwordx4 v152, s[50:51]
	s_addc_u32 s13, s51, 0
	s_add_i32 m0, s47, 0x14000
	v_lshl_or_b32 v146, v7, 11, v4
	global_load_lds_dwordx4 v148, s[12:13]
	s_add_i32 m0, s47, 0x16000
	s_add_u32 s48, s68, s10
	s_addc_u32 s49, s69, s11
	s_add_i32 s73, s47, 0x2000
	global_load_lds_dwordx4 v152, s[12:13]
	s_mov_b32 m0, s47
	s_add_u32 s10, s48, 0x40000
	v_lshl_or_b32 v150, v6, 11, v4
	global_load_lds_dwordx4 v146, s[48:49]
	s_mov_b32 m0, s73
	s_addc_u32 s11, s49, 0
	s_add_i32 s74, s47, 0x4000
	global_load_lds_dwordx4 v150, s[48:49]
	s_mov_b32 m0, s74
	s_add_i32 s75, s47, 0x6000
	global_load_lds_dwordx4 v146, s[10:11]
	s_mov_b32 m0, s75
	v_mov_b32_e32 v155, 0
	global_load_lds_dwordx4 v150, s[10:11]
	v_mov_b32_e32 v149, v155
	v_mov_b32_e32 v153, v155
	v_mov_b32_e32 v147, v155
	v_mov_b32_e32 v151, v155
	s_cmp_eq_u32 s0, 1
	v_writelane_b32 v250, s78, 0
	s_mov_b32 s76, 0
	s_mov_b32 s77, 0x10000
	v_lshl_add_u64 v[10:11], s[50:51], 0, v[148:149]
	v_lshl_add_u64 v[8:9], s[50:51], 0, v[152:153]
	v_lshl_add_u64 v[4:5], s[48:49], 0, v[146:147]
	s_cselect_b64 s[10:11], -1, 0
	s_cmp_lg_u32 s0, 1
	v_lshl_add_u64 v[6:7], s[48:49], 0, v[150:151]
	v_writelane_b32 v250, s79, 1
	s_cbranch_scc1 .LBB0_156
	s_barrier
